# G3 epilogue stores in scalar-base form: one 32-bit lane offset plus a scalar base advanced between the 8 stores (removes 8 v_mad_i64_i32 and the 64-bit adds per unit); stacked on stack31
# speedup vs baseline: 1.0008x; 1.0008x over previous
; __device__ __forceinline__ unsigned cvt_pk_bf16(float lo, float hi) { unsigned r; asm volatile("v_cvt_pk_bf16_f32 %0, %1, %2" : "=v"(r) : "v"(lo), "v"(hi)); return r; }
; #define x (arg_in(0))
; __device__ __forceinline__ float silu_mul(float g, float u) { return g * u * __builtin_amdgcn_rcpf(1.f + __builtin_amdgcn_exp2f(-1.4426950408889634f * g)); }
;     __device__ __forceinline__ void operator()(const f32x4 (&acc)[2][2][4][2], const Unit& u, int wr, int wc, int fr, int fq) const {
;         const int row0 = u.pm * BM + wr * 64 + fr, col0 = u.pn * HALF + wc * 32 + 8 * fq;
; #pragma unroll
;         for (int ai = 0; ai < 2; ++ai)
; #pragma unroll
;             for (int m = 0; m < 4; ++m) { bf16_t* rowp = O + (size_t)(row0 + ai * HALF + m * 16) * ldc + col0;
;                 const f32x4 g0 = acc[ai][0][m][0], g1 = acc[ai][0][m][1], u0 = acc[ai][1][m][0], u1 = acc[ai][1][m][1];
;                 u32x4 w; w.x = cvt_pk_bf16(silu_mul(g0[0], u0[0]), silu_mul(g0[1], u0[1])); w.y = cvt_pk_bf16(silu_mul(g0[2], u0[2]), silu_mul(g0[3], u0[3]));
;                 w.z = cvt_pk_bf16(silu_mul(g1[0], u1[0]), silu_mul(g1[1], u1[1])); w.w = cvt_pk_bf16(silu_mul(g1[2], u1[2]), silu_mul(g1[3], u1[3]));
;                 *(u32x4*)rowp = w; }
.LBB0_816:
	s_mov_b32 vcc_lo, 0xbfb8aa3b
	s_mov_b32 vcc_hi, 1.0
	s_mul_i32 s98, s27, 0x160000
	s_lshl_b32 s99, s26, 8
	s_add_u32 s98, s98, s99
	s_add_u32 s98, s44, s98
	s_addc_u32 s99, s45, 0
	v_mul_u32_u24_e32 v140, 0x1600, v144
	v_lshl_add_u32 v140, v146, 1, v140
	v_pk_mul_f32 v[120:121], v[124:125], v[120:121]
	v_pk_mul_f32 v[122:123], v[126:127], v[122:123]
	v_pk_mul_f32 v[112:113], v[116:117], v[112:113]
	v_pk_mul_f32 v[114:115], v[118:119], v[114:115]
	v_pk_mul_f32 v[124:125], v[124:125], vcc op_sel_hi:[1,0]
	v_pk_mul_f32 v[126:127], v[126:127], vcc op_sel_hi:[1,0]
	v_pk_mul_f32 v[116:117], v[116:117], vcc op_sel_hi:[1,0]
	v_pk_mul_f32 v[118:119], v[118:119], vcc op_sel_hi:[1,0]
	v_exp_f32_e32 v124, v124
	v_exp_f32_e32 v125, v125
	v_exp_f32_e32 v126, v126
	v_exp_f32_e32 v127, v127
	v_exp_f32_e32 v116, v116
	v_exp_f32_e32 v117, v117
	v_exp_f32_e32 v118, v118
	v_exp_f32_e32 v119, v119
	v_pk_add_f32 v[124:125], v[124:125], vcc op_sel:[0,1]
	v_pk_add_f32 v[126:127], v[126:127], vcc op_sel:[0,1]
	v_pk_add_f32 v[116:117], v[116:117], vcc op_sel:[0,1]
	v_pk_add_f32 v[118:119], v[118:119], vcc op_sel:[0,1]
	v_rcp_f32_e32 v124, v124
	v_rcp_f32_e32 v125, v125
	v_rcp_f32_e32 v126, v126
	v_rcp_f32_e32 v127, v127
	v_rcp_f32_e32 v116, v116
	v_rcp_f32_e32 v117, v117
	v_rcp_f32_e32 v118, v118
	v_rcp_f32_e32 v119, v119
	v_pk_mul_f32 v[120:121], v[124:125], v[120:121]
	v_pk_mul_f32 v[122:123], v[126:127], v[122:123]
	v_pk_mul_f32 v[112:113], v[116:117], v[112:113]
	v_pk_mul_f32 v[114:115], v[118:119], v[114:115]
	v_cvt_pk_bf16_f32 v120, v120, v121
	v_cvt_pk_bf16_f32 v121, v122, v123
	v_cvt_pk_bf16_f32 v122, v112, v113
	v_cvt_pk_bf16_f32 v123, v114, v115
	global_store_dwordx4 v140, v[120:123], s[98:99]
	s_add_u32 s98, s98, 0x16000
	s_addc_u32 s99, s99, 0
	v_pk_mul_f32 v[104:105], v[108:109], v[104:105]
	v_pk_mul_f32 v[106:107], v[110:111], v[106:107]
	v_pk_mul_f32 v[96:97], v[100:101], v[96:97]
	v_pk_mul_f32 v[98:99], v[102:103], v[98:99]
	v_pk_mul_f32 v[108:109], v[108:109], vcc op_sel_hi:[1,0]
	v_pk_mul_f32 v[110:111], v[110:111], vcc op_sel_hi:[1,0]
	v_pk_mul_f32 v[100:101], v[100:101], vcc op_sel_hi:[1,0]
	v_pk_mul_f32 v[102:103], v[102:103], vcc op_sel_hi:[1,0]
	v_exp_f32_e32 v108, v108
	v_exp_f32_e32 v109, v109
	v_exp_f32_e32 v110, v110
	v_exp_f32_e32 v111, v111
	v_exp_f32_e32 v100, v100
	v_exp_f32_e32 v101, v101
	v_exp_f32_e32 v102, v102
	v_exp_f32_e32 v103, v103
	v_pk_add_f32 v[108:109], v[108:109], vcc op_sel:[0,1]
	v_pk_add_f32 v[110:111], v[110:111], vcc op_sel:[0,1]
	v_pk_add_f32 v[100:101], v[100:101], vcc op_sel:[0,1]
	v_pk_add_f32 v[102:103], v[102:103], vcc op_sel:[0,1]
	v_rcp_f32_e32 v108, v108
	v_rcp_f32_e32 v109, v109
	v_rcp_f32_e32 v110, v110
	v_rcp_f32_e32 v111, v111
	v_rcp_f32_e32 v100, v100
	v_rcp_f32_e32 v101, v101
	v_rcp_f32_e32 v102, v102
	v_rcp_f32_e32 v103, v103
	v_pk_mul_f32 v[104:105], v[108:109], v[104:105]
	v_pk_mul_f32 v[106:107], v[110:111], v[106:107]
	v_pk_mul_f32 v[96:97], v[100:101], v[96:97]
	v_pk_mul_f32 v[98:99], v[102:103], v[98:99]
	v_cvt_pk_bf16_f32 v104, v104, v105
	v_cvt_pk_bf16_f32 v105, v106, v107
	v_cvt_pk_bf16_f32 v106, v96, v97
	v_cvt_pk_bf16_f32 v107, v98, v99
	global_store_dwordx4 v140, v[104:107], s[98:99]
	s_add_u32 s98, s98, 0x16000
	s_addc_u32 s99, s99, 0
	v_pk_mul_f32 v[88:89], v[92:93], v[88:89]
	v_pk_mul_f32 v[90:91], v[94:95], v[90:91]
	v_pk_mul_f32 v[80:81], v[84:85], v[80:81]
	v_pk_mul_f32 v[82:83], v[86:87], v[82:83]
	v_pk_mul_f32 v[92:93], v[92:93], vcc op_sel_hi:[1,0]
	v_pk_mul_f32 v[94:95], v[94:95], vcc op_sel_hi:[1,0]
	v_pk_mul_f32 v[84:85], v[84:85], vcc op_sel_hi:[1,0]
	v_pk_mul_f32 v[86:87], v[86:87], vcc op_sel_hi:[1,0]
	v_exp_f32_e32 v92, v92
	v_exp_f32_e32 v93, v93
	v_exp_f32_e32 v94, v94
	v_exp_f32_e32 v95, v95
	v_exp_f32_e32 v84, v84
	v_exp_f32_e32 v85, v85
	v_exp_f32_e32 v86, v86
	v_exp_f32_e32 v87, v87
	v_pk_add_f32 v[92:93], v[92:93], vcc op_sel:[0,1]
	v_pk_add_f32 v[94:95], v[94:95], vcc op_sel:[0,1]
	v_pk_add_f32 v[84:85], v[84:85], vcc op_sel:[0,1]
	v_pk_add_f32 v[86:87], v[86:87], vcc op_sel:[0,1]
	v_rcp_f32_e32 v92, v92
	v_rcp_f32_e32 v93, v93
	v_rcp_f32_e32 v94, v94
	v_rcp_f32_e32 v95, v95
	v_rcp_f32_e32 v84, v84
	v_rcp_f32_e32 v85, v85
	v_rcp_f32_e32 v86, v86
	v_rcp_f32_e32 v87, v87
	v_pk_mul_f32 v[88:89], v[92:93], v[88:89]
	v_pk_mul_f32 v[90:91], v[94:95], v[90:91]
	v_pk_mul_f32 v[80:81], v[84:85], v[80:81]
	v_pk_mul_f32 v[82:83], v[86:87], v[82:83]
	v_cvt_pk_bf16_f32 v88, v88, v89
	v_cvt_pk_bf16_f32 v89, v90, v91
	v_cvt_pk_bf16_f32 v90, v80, v81
	v_cvt_pk_bf16_f32 v91, v82, v83
	global_store_dwordx4 v140, v[88:91], s[98:99]
	s_add_u32 s98, s98, 0x16000
	s_addc_u32 s99, s99, 0
	v_pk_mul_f32 v[72:73], v[76:77], v[72:73]
	v_pk_mul_f32 v[74:75], v[78:79], v[74:75]
	v_pk_mul_f32 v[64:65], v[68:69], v[64:65]
	v_pk_mul_f32 v[66:67], v[70:71], v[66:67]
	v_pk_mul_f32 v[76:77], v[76:77], vcc op_sel_hi:[1,0]
	v_pk_mul_f32 v[78:79], v[78:79], vcc op_sel_hi:[1,0]
	v_pk_mul_f32 v[68:69], v[68:69], vcc op_sel_hi:[1,0]
	v_pk_mul_f32 v[70:71], v[70:71], vcc op_sel_hi:[1,0]
	v_exp_f32_e32 v76, v76
	v_exp_f32_e32 v77, v77
	v_exp_f32_e32 v78, v78
	v_exp_f32_e32 v79, v79
	v_exp_f32_e32 v68, v68
	v_exp_f32_e32 v69, v69
	v_exp_f32_e32 v70, v70
	v_exp_f32_e32 v71, v71
	v_pk_add_f32 v[76:77], v[76:77], vcc op_sel:[0,1]
	v_pk_add_f32 v[78:79], v[78:79], vcc op_sel:[0,1]
	v_pk_add_f32 v[68:69], v[68:69], vcc op_sel:[0,1]
	v_pk_add_f32 v[70:71], v[70:71], vcc op_sel:[0,1]
	v_rcp_f32_e32 v76, v76
	v_rcp_f32_e32 v77, v77
	v_rcp_f32_e32 v78, v78
	v_rcp_f32_e32 v79, v79
	v_rcp_f32_e32 v68, v68
	v_rcp_f32_e32 v69, v69
	v_rcp_f32_e32 v70, v70
	v_rcp_f32_e32 v71, v71
	v_pk_mul_f32 v[72:73], v[76:77], v[72:73]
; __device__ __forceinline__ unsigned cvt_pk_bf16(float lo, float hi) { unsigned r; asm volatile("v_cvt_pk_bf16_f32 %0, %1, %2" : "=v"(r) : "v"(lo), "v"(hi)); return r; }
; #define x (arg_in(0))
; __device__ __forceinline__ float silu_mul(float g, float u) { return g * u * __builtin_amdgcn_rcpf(1.f + __builtin_amdgcn_exp2f(-1.4426950408889634f * g)); }
;     __device__ __forceinline__ void operator()(const f32x4 (&acc)[2][2][4][2], const Unit& u, int wr, int wc, int fr, int fq) const {
;         const int row0 = u.pm * BM + wr * 64 + fr, col0 = u.pn * HALF + wc * 32 + 8 * fq;
; #pragma unroll
;         for (int ai = 0; ai < 2; ++ai)
; #pragma unroll
;             for (int m = 0; m < 4; ++m) { bf16_t* rowp = O + (size_t)(row0 + ai * HALF + m * 16) * ldc + col0;
;                 const f32x4 g0 = acc[ai][0][m][0], g1 = acc[ai][0][m][1], u0 = acc[ai][1][m][0], u1 = acc[ai][1][m][1];
;                 u32x4 w; w.x = cvt_pk_bf16(silu_mul(g0[0], u0[0]), silu_mul(g0[1], u0[1])); w.y = cvt_pk_bf16(silu_mul(g0[2], u0[2]), silu_mul(g0[3], u0[3]));
;                 w.z = cvt_pk_bf16(silu_mul(g1[0], u1[0]), silu_mul(g1[1], u1[1])); w.w = cvt_pk_bf16(silu_mul(g1[2], u1[2]), silu_mul(g1[3], u1[3]));
;                 *(u32x4*)rowp = w; }
	v_pk_mul_f32 v[74:75], v[78:79], v[74:75]
	v_pk_mul_f32 v[64:65], v[68:69], v[64:65]
	v_pk_mul_f32 v[66:67], v[70:71], v[66:67]
	v_cvt_pk_bf16_f32 v72, v72, v73
	v_cvt_pk_bf16_f32 v73, v74, v75
	v_cvt_pk_bf16_f32 v74, v64, v65
	v_cvt_pk_bf16_f32 v75, v66, v67
	global_store_dwordx4 v140, v[72:75], s[98:99]
	s_add_u32 s98, s98, 0x6e000
	s_addc_u32 s99, s99, 0
	v_pk_mul_f32 v[56:57], v[60:61], v[56:57]
	v_pk_mul_f32 v[58:59], v[62:63], v[58:59]
	v_pk_mul_f32 v[48:49], v[52:53], v[48:49]
	v_pk_mul_f32 v[50:51], v[54:55], v[50:51]
	v_pk_mul_f32 v[60:61], v[60:61], vcc op_sel_hi:[1,0]
	v_pk_mul_f32 v[62:63], v[62:63], vcc op_sel_hi:[1,0]
	v_pk_mul_f32 v[52:53], v[52:53], vcc op_sel_hi:[1,0]
	v_pk_mul_f32 v[54:55], v[54:55], vcc op_sel_hi:[1,0]
	v_exp_f32_e32 v60, v60
	v_exp_f32_e32 v61, v61
	v_exp_f32_e32 v62, v62
	v_exp_f32_e32 v63, v63
	v_exp_f32_e32 v52, v52
	v_exp_f32_e32 v53, v53
	v_exp_f32_e32 v54, v54
	v_exp_f32_e32 v55, v55
	v_pk_add_f32 v[60:61], v[60:61], vcc op_sel:[0,1]
	v_pk_add_f32 v[62:63], v[62:63], vcc op_sel:[0,1]
	v_pk_add_f32 v[52:53], v[52:53], vcc op_sel:[0,1]
	v_pk_add_f32 v[54:55], v[54:55], vcc op_sel:[0,1]
	v_rcp_f32_e32 v60, v60
	v_rcp_f32_e32 v61, v61
	v_rcp_f32_e32 v62, v62
	v_rcp_f32_e32 v63, v63
	v_rcp_f32_e32 v52, v52
	v_rcp_f32_e32 v53, v53
	v_rcp_f32_e32 v54, v54
	v_rcp_f32_e32 v55, v55
	v_pk_mul_f32 v[56:57], v[60:61], v[56:57]
	v_pk_mul_f32 v[58:59], v[62:63], v[58:59]
	v_pk_mul_f32 v[48:49], v[52:53], v[48:49]
	v_pk_mul_f32 v[50:51], v[54:55], v[50:51]
	v_cvt_pk_bf16_f32 v56, v56, v57
	v_cvt_pk_bf16_f32 v57, v58, v59
	v_cvt_pk_bf16_f32 v58, v48, v49
	v_cvt_pk_bf16_f32 v59, v50, v51
	global_store_dwordx4 v140, v[56:59], s[98:99]
	s_add_u32 s98, s98, 0x16000
	s_addc_u32 s99, s99, 0
	v_pk_mul_f32 v[40:41], v[44:45], v[40:41]
	v_pk_mul_f32 v[42:43], v[46:47], v[42:43]
	v_pk_mul_f32 v[32:33], v[36:37], v[32:33]
	v_pk_mul_f32 v[34:35], v[38:39], v[34:35]
	v_pk_mul_f32 v[44:45], v[44:45], vcc op_sel_hi:[1,0]
	v_pk_mul_f32 v[46:47], v[46:47], vcc op_sel_hi:[1,0]
	v_pk_mul_f32 v[36:37], v[36:37], vcc op_sel_hi:[1,0]
	v_pk_mul_f32 v[38:39], v[38:39], vcc op_sel_hi:[1,0]
	v_exp_f32_e32 v44, v44
	v_exp_f32_e32 v45, v45
	v_exp_f32_e32 v46, v46
	v_exp_f32_e32 v47, v47
	v_exp_f32_e32 v36, v36
	v_exp_f32_e32 v37, v37
	v_exp_f32_e32 v38, v38
	v_exp_f32_e32 v39, v39
	v_pk_add_f32 v[44:45], v[44:45], vcc op_sel:[0,1]
	v_pk_add_f32 v[46:47], v[46:47], vcc op_sel:[0,1]
	v_pk_add_f32 v[36:37], v[36:37], vcc op_sel:[0,1]
	v_pk_add_f32 v[38:39], v[38:39], vcc op_sel:[0,1]
	v_rcp_f32_e32 v44, v44
	v_rcp_f32_e32 v45, v45
	v_rcp_f32_e32 v46, v46
	v_rcp_f32_e32 v47, v47
	v_rcp_f32_e32 v36, v36
	v_rcp_f32_e32 v37, v37
	v_rcp_f32_e32 v38, v38
	v_rcp_f32_e32 v39, v39
	v_pk_mul_f32 v[40:41], v[44:45], v[40:41]
	v_pk_mul_f32 v[42:43], v[46:47], v[42:43]
	v_pk_mul_f32 v[32:33], v[36:37], v[32:33]
	v_pk_mul_f32 v[34:35], v[38:39], v[34:35]
	v_cvt_pk_bf16_f32 v40, v40, v41
	v_cvt_pk_bf16_f32 v41, v42, v43
	v_cvt_pk_bf16_f32 v42, v32, v33
	v_cvt_pk_bf16_f32 v43, v34, v35
	global_store_dwordx4 v140, v[40:43], s[98:99]
	s_add_u32 s98, s98, 0x16000
	s_addc_u32 s99, s99, 0
	v_pk_mul_f32 v[24:25], v[28:29], v[24:25]
	v_pk_mul_f32 v[26:27], v[30:31], v[26:27]
	v_pk_mul_f32 v[16:17], v[20:21], v[16:17]
	v_pk_mul_f32 v[18:19], v[22:23], v[18:19]
	v_pk_mul_f32 v[28:29], v[28:29], vcc op_sel_hi:[1,0]
	v_pk_mul_f32 v[30:31], v[30:31], vcc op_sel_hi:[1,0]
	v_pk_mul_f32 v[20:21], v[20:21], vcc op_sel_hi:[1,0]
	v_pk_mul_f32 v[22:23], v[22:23], vcc op_sel_hi:[1,0]
	v_exp_f32_e32 v28, v28
	v_exp_f32_e32 v29, v29
	v_exp_f32_e32 v30, v30
	v_exp_f32_e32 v31, v31
	v_exp_f32_e32 v20, v20
	v_exp_f32_e32 v21, v21
	v_exp_f32_e32 v22, v22
	v_exp_f32_e32 v23, v23
	v_pk_add_f32 v[28:29], v[28:29], vcc op_sel:[0,1]
	v_pk_add_f32 v[30:31], v[30:31], vcc op_sel:[0,1]
	v_pk_add_f32 v[20:21], v[20:21], vcc op_sel:[0,1]
	v_pk_add_f32 v[22:23], v[22:23], vcc op_sel:[0,1]
	v_rcp_f32_e32 v28, v28
	v_rcp_f32_e32 v29, v29
	v_rcp_f32_e32 v30, v30
	v_rcp_f32_e32 v31, v31
	v_rcp_f32_e32 v20, v20
	v_rcp_f32_e32 v21, v21
	v_rcp_f32_e32 v22, v22
	v_rcp_f32_e32 v23, v23
	v_pk_mul_f32 v[24:25], v[28:29], v[24:25]
	v_pk_mul_f32 v[26:27], v[30:31], v[26:27]
	v_pk_mul_f32 v[16:17], v[20:21], v[16:17]
	v_pk_mul_f32 v[18:19], v[22:23], v[18:19]
	v_cvt_pk_bf16_f32 v24, v24, v25
	v_cvt_pk_bf16_f32 v25, v26, v27
	v_cvt_pk_bf16_f32 v26, v16, v17
	v_cvt_pk_bf16_f32 v27, v18, v19
	global_store_dwordx4 v140, v[24:27], s[98:99]
	s_add_u32 s98, s98, 0x16000
	s_addc_u32 s99, s99, 0
	v_pk_mul_f32 v[8:9], v[12:13], v[8:9]
	v_pk_mul_f32 v[10:11], v[14:15], v[10:11]
	v_pk_mul_f32 v[0:1], v[4:5], v[0:1]
	v_pk_mul_f32 v[2:3], v[6:7], v[2:3]
	v_pk_mul_f32 v[12:13], v[12:13], vcc op_sel_hi:[1,0]
	v_pk_mul_f32 v[14:15], v[14:15], vcc op_sel_hi:[1,0]
	v_pk_mul_f32 v[4:5], v[4:5], vcc op_sel_hi:[1,0]
	v_pk_mul_f32 v[6:7], v[6:7], vcc op_sel_hi:[1,0]
	v_exp_f32_e32 v12, v12
	v_exp_f32_e32 v13, v13
	v_exp_f32_e32 v14, v14
	v_exp_f32_e32 v15, v15
	v_exp_f32_e32 v4, v4
	v_exp_f32_e32 v5, v5
	v_exp_f32_e32 v6, v6
	v_exp_f32_e32 v7, v7
	v_pk_add_f32 v[12:13], v[12:13], vcc op_sel:[0,1]
	v_pk_add_f32 v[14:15], v[14:15], vcc op_sel:[0,1]
	v_pk_add_f32 v[4:5], v[4:5], vcc op_sel:[0,1]
	v_pk_add_f32 v[6:7], v[6:7], vcc op_sel:[0,1]
	v_rcp_f32_e32 v12, v12
	v_rcp_f32_e32 v13, v13
	v_rcp_f32_e32 v14, v14
	v_rcp_f32_e32 v15, v15
	v_rcp_f32_e32 v4, v4
	v_rcp_f32_e32 v5, v5
	v_rcp_f32_e32 v6, v6
	v_rcp_f32_e32 v7, v7
	v_pk_mul_f32 v[8:9], v[12:13], v[8:9]
	v_pk_mul_f32 v[10:11], v[14:15], v[10:11]
	v_pk_mul_f32 v[0:1], v[4:5], v[0:1]
	v_pk_mul_f32 v[2:3], v[6:7], v[2:3]
	s_mov_b64 s[36:37], -1
	s_andn2_b64 vcc, exec, s[38:39]
	s_mov_b64 s[30:31], 0x3200000
	s_mov_b32 s34, s74
	v_cvt_pk_bf16_f32 v8, v8, v9
	v_cvt_pk_bf16_f32 v9, v10, v11
	v_cvt_pk_bf16_f32 v10, v0, v1
	v_cvt_pk_bf16_f32 v11, v2, v3
	global_store_dwordx4 v140, v[8:11], s[98:99]
	s_cbranch_vccnz .LBB0_809
	s_andn2_b64 vcc, exec, s[42:43]
	s_cbranch_vccnz .LBB0_808
	s_barrier
	s_branch .LBB0_808
